# v23: mixers units no longer wait at entry for the previous unit's stores (the unit's own load wait covers them)
# speedup vs baseline: 1.0319x; 1.0046x over previous
; __device__ __forceinline__ void short_unit_p(const bf16* __restrict__ Z, bf16* __restrict__ CAT, float* __restrict__ news, const float* __restrict__ sw, int seq, int t0, int h, int lane) {
;     const int rr = lane >> 3, cg = lane & 7, c0 = h * 64 + cg * 8, tb = t0 + rr * 8;
;     const size_t rowbase = (size_t)seq * SEQ;
;     const bf16* zb = Z + (rowbase + tb) * ZP + c0;
;     v4u Bv[8], Cv[10], Hv[10];
; #pragma unroll
;     for (int j = 0; j < 10; ++j) { const int dj = j - 2; const bool ok = (tb + dj >= 0);
;         Cv[j] = ok ? ld16(zb + (long)dj * ZP + 1536) : (v4u){0u, 0u, 0u, 0u}; Hv[j] = ok ? ld16(zb + (long)dj * ZP + 1792) : (v4u){0u, 0u, 0u, 0u};
;         if (j >= 2) Bv[j - 2] = ld16(zb + (long)dj * ZP + 1280); }
.LBB0_141:
	s_andn2_b64 vcc, exec, s[4:5]
	s_mov_b32 s2, 0
	s_cbranch_vccnz .LBB0_359
	s_add_i32 s2, s87, 0xfffff600
	s_lshl_b32 s4, s87, 4
	s_and_b32 s10, s87, 3
	s_bfe_u32 s8, s2, 0x30007
	s_and_b32 s9, s4, 0x7c0
	s_cmpk_gt_u32 s2, 0x3ff
	s_mov_b64 s[4:5], -1
	s_cbranch_scc0 .LBB0_166
	s_mul_i32 s2, s8, 0x1040000
	s_add_u32 s2, s64, s2
	s_addc_u32 s5, s65, 0
	s_mul_i32 s4, s8, 0xff7c0000
	v_and_b32_e32 v125, -8, v124
	s_mul_hi_i32 s6, s8, 0xff7c0000
	s_add_u32 s4, s2, s4
	s_nop 0
	v_add_u32_e32 v2, s9, v125
	s_addc_u32 s5, s5, s6
	s_lshl_b32 s2, s10, 6
	s_nop 0
	v_lshlrev_b32_e32 v0, 3, v124
	s_lshl_b32 s84, s8, 11
	v_ashrrev_i32_e32 v3, 31, v2
	v_and_or_b32 v80, v0, 56, s2
	v_lshl_add_u64 v[136:137], s[84:85], 0, v[2:3]
	v_mov_b64_e32 v[0:1], s[4:5]
	v_mad_u64_u32 v[0:1], s[6:7], v136, s78, v[0:1]
	v_mad_i32_i24 v1, v137, s78, v1
	v_lshlrev_b32_e32 v128, 1, v80
	v_lshl_add_u64 v[126:127], v[0:1], 0, v[128:129]
	v_cmp_lt_i32_e32 vcc, 1, v2
	v_mov_b32_e32 v28, 0
	v_mov_b32_e32 v64, 0
	v_mov_b32_e32 v65, 0
	v_mov_b32_e32 v66, 0
	v_mov_b32_e32 v67, 0
	v_mov_b32_e32 v68, 0
	v_mov_b32_e32 v69, 0
	v_mov_b32_e32 v70, 0
	v_mov_b32_e32 v71, 0
	s_and_saveexec_b64 s[6:7], vcc
	s_cbranch_execz .LBB0_145
	v_add_co_u32_e32 v0, vcc, 0xfffff000, v126
	s_nop 1
	v_addc_co_u32_e32 v1, vcc, -1, v127, vcc
	global_load_dwordx4 v[64:67], v[0:1], off offset:-1280
	global_load_dwordx4 v[68:71], v[0:1], off offset:-768

; template <int W>
; __device__ __forceinline__ void pool_unit_p(const bf16* __restrict__ Z, bf16* __restrict__ CAT, float* __restrict__ newp, int seq, int t0, int g, int lane) {
;     const int rr = lane >> 3, cg = lane & 7, c0 = g * 64 + cg * 8, tb = t0 + rr * 8;
;     const size_t rowbase = (size_t)seq * SEQ;
;     const bf16* zb = Z + (rowbase + tb) * ZP + c0;
;     v4u raw[W + 7];
; #pragma unroll
;     for (int j = 0; j < W + 7; ++j) { const int dj = j - (W - 1); raw[j] = (tb + dj >= 0) ? ld16(zb + (long)dj * ZP) : (v4u){0u, 0u, 0u, 0u}; }
.LBB0_166:
	s_and_b64 vcc, exec, s[4:5]
	s_cbranch_vccz .LBB0_358
	s_cmp_lt_i32 s10, 2
	s_mov_b64 s[4:5], -1
	s_cbranch_scc1 .LBB0_281
	s_cmp_gt_i32 s10, 2
	s_cbranch_scc0 .LBB0_232
	s_mul_i32 s2, s8, 0x1040000
	s_add_u32 s4, s64, s2
	s_nop 0
	v_lshlrev_b32_e32 v0, 3, v124
	s_addc_u32 s5, s65, 0
	s_mul_i32 s6, s8, 0xff7c0000
	v_and_b32_e32 v98, 56, v0
	v_and_b32_e32 v0, -8, v124
	s_mul_hi_i32 s2, s8, 0xff7c0000
	s_add_u32 s6, s4, s6
	v_add_u32_e32 v92, s9, v0
	s_addc_u32 s7, s5, s2
	s_lshl_b32 s84, s8, 11
	v_ashrrev_i32_e32 v93, 31, v92
	v_lshl_add_u64 v[94:95], s[84:85], 0, v[92:93]
	v_mov_b64_e32 v[0:1], s[6:7]
	v_mad_u64_u32 v[0:1], s[6:7], v94, s78, v[0:1]
	v_mad_i32_i24 v1, v95, s78, v1
	v_lshlrev_b32_e32 v128, 1, v98
	v_lshl_add_u64 v[0:1], v[0:1], 0, v[128:129]
	s_mov_b64 s[6:7], 0x180
	v_lshl_add_u64 v[96:97], v[0:1], 0, s[6:7]
	v_cmp_lt_i32_e32 vcc, 14, v92
	v_mov_b32_e32 v16, 0
	v_mov_b32_e32 v20, 0
	v_mov_b32_e32 v21, 0
	v_mov_b32_e32 v22, 0
	v_mov_b32_e32 v23, 0
	s_and_saveexec_b64 s[6:7], vcc
	s_cbranch_execz .LBB0_171
	v_add_co_u32_e32 v2, vcc, 0xffff1000, v96
	s_nop 1
	v_addc_co_u32_e32 v3, vcc, -1, v97, vcc
	global_load_dwordx4 v[20:23], v[2:3], off offset:-1920

; template <int W>
; __device__ __forceinline__ void pool_unit_p(const bf16* __restrict__ Z, bf16* __restrict__ CAT, float* __restrict__ newp, int seq, int t0, int g, int lane) {
;     const int rr = lane >> 3, cg = lane & 7, c0 = g * 64 + cg * 8, tb = t0 + rr * 8;
;     const size_t rowbase = (size_t)seq * SEQ;
;     const bf16* zb = Z + (rowbase + tb) * ZP + c0;
;     v4u raw[W + 7];
; #pragma unroll
;     for (int j = 0; j < W + 7; ++j) { const int dj = j - (W - 1); raw[j] = (tb + dj >= 0) ? ld16(zb + (long)dj * ZP) : (v4u){0u, 0u, 0u, 0u}; }
.LBB0_232:
	s_and_b64 vcc, exec, s[4:5]
	s_cbranch_vccz .LBB0_280
	s_mul_i32 s2, s8, 0x1040000
	s_add_u32 s4, s64, s2
	s_nop 0
	v_lshlrev_b32_e32 v0, 3, v124
	s_addc_u32 s5, s65, 0
	s_mul_i32 s6, s8, 0xff7c0000
	v_and_b32_e32 v66, 56, v0
	v_and_b32_e32 v0, -8, v124
	s_mul_hi_i32 s2, s8, 0xff7c0000
	s_add_u32 s6, s4, s6
	v_add_u32_e32 v60, s9, v0
	s_addc_u32 s7, s5, s2
	s_lshl_b32 s84, s8, 11
	v_ashrrev_i32_e32 v61, 31, v60
	v_lshl_add_u64 v[62:63], s[84:85], 0, v[60:61]
	v_mov_b64_e32 v[0:1], s[6:7]
	v_mad_u64_u32 v[0:1], s[6:7], v62, s78, v[0:1]
	v_mad_i32_i24 v1, v63, s78, v1
	v_lshlrev_b32_e32 v128, 1, v66
	v_lshl_add_u64 v[0:1], v[0:1], 0, v[128:129]
	s_mov_b64 s[6:7], 0x100
	v_lshl_add_u64 v[64:65], v[0:1], 0, s[6:7]
	v_cmp_lt_i32_e32 vcc, 6, v60
	v_mov_b32_e32 v24, 0
	v_mov_b32_e32 v28, 0
	v_mov_b32_e32 v29, 0
	v_mov_b32_e32 v30, 0
	v_mov_b32_e32 v31, 0
	s_and_saveexec_b64 s[6:7], vcc
	s_cbranch_execz .LBB0_235
	v_add_co_u32_e32 v2, vcc, 0xffff9000, v64
	s_nop 1
	v_addc_co_u32_e32 v3, vcc, -1, v65, vcc
	global_load_dwordx4 v[28:31], v[2:3], off offset:-896

; template <int W>
; __device__ __forceinline__ void pool_unit_p(const bf16* __restrict__ Z, bf16* __restrict__ CAT, float* __restrict__ newp, int seq, int t0, int g, int lane) {
;     const int rr = lane >> 3, cg = lane & 7, c0 = g * 64 + cg * 8, tb = t0 + rr * 8;
;     const size_t rowbase = (size_t)seq * SEQ;
;     const bf16* zb = Z + (rowbase + tb) * ZP + c0;
;     v4u raw[W + 7];
; #pragma unroll
;     for (int j = 0; j < W + 7; ++j) { const int dj = j - (W - 1); raw[j] = (tb + dj >= 0) ? ld16(zb + (long)dj * ZP) : (v4u){0u, 0u, 0u, 0u}; }
.LBB0_281:
	s_andn2_b64 vcc, exec, s[4:5]
	s_cbranch_vccnz .LBB0_358
	s_nop 0
	v_and_b32_e32 v0, -8, v124
	s_mov_b64 s[4:5], -1
	s_cmp_eq_u32 s10, 1
	s_mul_i32 s11, s8, 0x1040000
	s_mul_hi_i32 s2, s8, 0xff7c0000
	s_mul_i32 s10, s8, 0xff7c0000
	v_add_u32_e32 v48, s9, v0
	s_cbranch_scc1 .LBB0_318
	s_add_u32 s4, s64, s11
	s_addc_u32 s5, s65, 0
	s_add_u32 s6, s4, s10
	s_addc_u32 s7, s5, s2
	v_lshlrev_b32_e32 v0, 3, v124
	s_lshl_b32 s84, s8, 11
	v_ashrrev_i32_e32 v49, 31, v48
	v_and_b32_e32 v40, 56, v0
	v_lshl_add_u64 v[36:37], s[84:85], 0, v[48:49]
	v_mov_b64_e32 v[0:1], s[6:7]
	v_mad_u64_u32 v[0:1], s[6:7], v36, s78, v[0:1]
	v_mad_i32_i24 v1, v37, s78, v1
	v_lshlrev_b32_e32 v128, 1, v40
	v_lshl_add_u64 v[38:39], v[0:1], 0, v[128:129]
	v_mov_b32_e32 v28, 0
	v_cmp_lt_i32_e32 vcc, 0, v48
	v_mov_b32_e32 v32, 0
	v_mov_b32_e32 v33, 0
	v_mov_b32_e32 v34, 0
	v_mov_b32_e32 v35, 0
	s_and_saveexec_b64 s[6:7], vcc
	s_cbranch_execz .LBB0_285
	v_add_co_u32_e32 v0, vcc, 0xfffff000, v38
	s_nop 1
	v_addc_co_u32_e32 v1, vcc, -1, v39, vcc
	global_load_dwordx4 v[32:35], v[0:1], off offset:-128

; __device__ __forceinline__ void conv_unit_p(const bf16* __restrict__ Z, bf16* __restrict__ CAT, float* __restrict__ newc, ...
;     const int rr = lane >> 3, cg = lane & 7, c0 = h * 64 + cg * 8;
;     const size_t rowbase = (size_t)seq * SEQ;
;     const bool last = (t0 + 32 == SEQ);
;     const int c = h * 64 + lane;
;     float wk[31];
; #pragma unroll
;     for (int k = 0; k < 31; ++k) wk[k] = cw[k * GW + c];
;     const float bias = cb[c];
;     { v4u pv[8], gv[8];
; #pragma unroll
;       for (int j = 0; j < 8; ++j) { const int r = 8 * j + rr, sx = t0 - 30 + r; const bool ok = (sx >= 0 && r < 62);
;           const bf16* zp = Z + (rowbase + (ok ? sx : 0)) * ZP + c0;
;           pv[j] = ok ? ld16(zp + 256) : (v4u){0u, 0u, 0u, 0u}; gv[j] = ok ? ld16(zp + 512) : (v4u){0u, 0u, 0u, 0u}; }
.LBB0_360:
	s_andn2_b64 vcc, exec, s[4:5]
	s_cbranch_vccnz .LBB0_412
	s_add_i32 s2, s87, 0xfffffe00
	s_lshr_b32 s84, s2, 8
	s_lshl_b32 s2, s87, 3
	s_and_b32 s74, s2, 0x7e0
	s_mul_i32 s4, s84, 0x1040000
	s_mul_hi_u32 s2, s84, 0x1040000
	s_add_u32 s4, s64, s4
	s_addc_u32 s2, s65, s2
	s_mul_i32 s6, s84, 0xff7c0000
	s_mul_hi_i32 s5, s84, 0xff7c0000
	s_add_u32 s70, s4, s6
	s_addc_u32 s71, s2, s5
	s_lshl_b32 s2, s87, 6
	s_and_b32 s2, s2, 0xc0
	s_nop 0
	v_add_u32_e32 v0, s2, v124
	v_ashrrev_i32_e32 v1, 31, v0
	v_lshlrev_b64 v[0:1], 2, v[0:1]
	v_lshl_add_u64 v[2:3], s[52:53], 0, v[0:1]
	v_add_co_u32_e32 v4, vcc, s30, v2
	v_lshl_add_u64 v[0:1], s[44:45], 0, v[0:1]
	s_nop 0
	v_addc_co_u32_e32 v5, vcc, 0, v3, vcc
	v_add_co_u32_e32 v6, vcc, s21, v2
	v_ashrrev_i32_e32 v86, 3, v124
	s_nop 0
	v_addc_co_u32_e32 v7, vcc, 0, v3, vcc
	v_add_co_u32_e32 v8, vcc, s31, v2
	v_mov_b32_e32 v65, v129
	s_nop 0
	v_addc_co_u32_e32 v9, vcc, 0, v3, vcc
	v_add_co_u32_e32 v10, vcc, s28, v2
	v_cmp_gt_i32_e64 s[18:19], 62, v86
	s_nop 0
	v_addc_co_u32_e32 v11, vcc, 0, v3, vcc
	global_load_dword v87, v[2:3], off
	global_load_dword v88, v[2:3], off offset:1024
	global_load_dword v89, v[2:3], off offset:2048
	global_load_dword v90, v[2:3], off offset:3072
	global_load_dword v91, v[4:5], off offset:1024
	global_load_dword v92, v[4:5], off offset:2048
	global_load_dword v93, v[4:5], off offset:3072
	global_load_dword v94, v[8:9], off offset:1024
	global_load_dword v95, v[6:7], off offset:-4096
	global_load_dword v96, v[6:7], off
	global_load_dword v97, v[6:7], off offset:1024
	global_load_dword v98, v[6:7], off offset:2048
	global_load_dword v99, v[6:7], off offset:3072
	global_load_dword v100, v[10:11], off offset:-4096
	global_load_dword v101, v[10:11], off
	global_load_dword v102, v[10:11], off offset:1024
	v_add_co_u32_e32 v4, vcc, s36, v2
	s_lshl_b64 s[4:5], s[84:85], 11
	s_nop 0
	v_addc_co_u32_e32 v5, vcc, 0, v3, vcc
	v_add_co_u32_e32 v6, vcc, s29, v2
	v_mov_b32_e32 v44, 0
	s_nop 0
	v_addc_co_u32_e32 v7, vcc, 0, v3, vcc
	v_add_co_u32_e32 v2, vcc, s37, v2
	global_load_dword v103, v[10:11], off offset:2048
	global_load_dword v104, v[10:11], off offset:3072
	global_load_dword v105, v[6:7], off offset:-4096
	global_load_dword v106, v[6:7], off
	global_load_dword v107, v[6:7], off offset:1024
	global_load_dword v108, v[6:7], off offset:2048
	global_load_dword v109, v[6:7], off offset:3072
	v_addc_co_u32_e32 v3, vcc, 0, v3, vcc
	global_load_dword v110, v[8:9], off offset:2048
	global_load_dword v111, v[8:9], off offset:3072
	global_load_dword v112, v[4:5], off offset:1024
	global_load_dword v113, v[4:5], off offset:2048
	global_load_dword v114, v[4:5], off offset:3072
	global_load_dword v115, v[2:3], off
	global_load_dword v116, v[2:3], off offset:1024
	global_load_dword v117, v[2:3], off offset:2048
	global_load_dword v118, v[0:1], off
	v_lshlrev_b32_e32 v0, 3, v124
	v_and_b32_e32 v73, 56, v0
	v_or_b32_e32 v72, s2, v73
	s_sub_i32 s2, s74, 30
	v_add_u32_e32 v84, s2, v86
	v_lshlrev_b32_e32 v64, 1, v72
	v_cmp_lt_i32_e32 vcc, -1, v84
	v_lshl_add_u64 v[70:71], s[70:71], 0, v[64:65]
	s_and_b64 s[8:9], s[18:19], vcc
	v_mov_b32_e32 v56, 0
	v_mov_b32_e32 v57, 0
	v_mov_b32_e32 v58, 0
	v_mov_b32_e32 v59, 0
	v_mov_b32_e32 v60, 0
	v_mov_b32_e32 v61, 0
	v_mov_b32_e32 v62, 0
	v_mov_b32_e32 v63, 0
	s_and_saveexec_b64 s[6:7], s[8:9]
	s_cbranch_execz .LBB0_363
	v_mov_b32_e32 v85, v129
	v_lshl_add_u64 v[0:1], s[4:5], 0, v[84:85]
	v_mad_u64_u32 v[2:3], s[8:9], v0, s78, v[70:71]
	v_mad_u32_u24 v3, v1, s78, v3
	global_load_dwordx4 v[56:59], v[2:3], off offset:512
	global_load_dwordx4 v[60:63], v[2:3], off offset:1024

; __device__ __forceinline__ void sgu_unit(const bf16* __restrict__ Z, bf16* __restrict__ CAT, const bf16* __restrict__ Wb, const float* __restrict__ lg, const float* __restrict__ lb,
;                                          const float* __restrict__ sb, int chunk, int h, LAS bf16* vT, int lane) {
;     const size_t r0 = (size_t)chunk * 128;
;     const int fr = lane & 15, fq = lane >> 4;
;     bf16x8 wf[8][4];
; #pragma unroll
;     for (int mt = 0; mt < 8; ++mt)
; #pragma unroll
;         for (int ks = 0; ks < 4; ++ks) if (ks * 32 <= mt * 16 + 15) wf[mt][ks] = *(const bf16x8*)(Wb + ((size_t)(h * 128 + mt * 16 + fr) * 128 + ks * 32 + fq * 8));
;     { const int rr = lane >> 3, cg = lane & 7, c0 = h * 64 + cg * 8;
;       float gg[8], bb[8];
; #pragma unroll
;       for (int i = 0; i < 8; ++i) { gg[i] = lg[c0 + i]; bb[i] = lb[c0 + i]; }
; #pragma unroll 1
;       for (int jh = 0; jh < 16; jh += 8) {
;           v4u raw[8];
; #pragma unroll
;           for (int j = 0; j < 8; ++j) raw[j] = ld16(Z + (r0 + 8 * (jh + j) + rr) * ZP + 1024 + c0);
.LBB0_413:
	s_andn2_b64 vcc, exec, s[4:5]
	s_cbranch_vccnz .LBB0_417
	s_ashr_i32 s12, s87, 6
	s_ashr_i32 s13, s12, 31
	s_mul_i32 s4, s12, 0x1040000
	s_mul_hi_i32 s2, s12, 0x1040000
	s_add_u32 s4, s64, s4
	s_addc_u32 s5, s65, s2
	s_mul_i32 s6, s12, 0xff7c0000
	s_mul_hi_i32 s2, s12, 0xff7c0000
	s_add_u32 s10, s4, s6
	s_addc_u32 s11, s5, s2
	s_and_b32 s2, s87, 3
	v_ashrrev_i32_e32 v157, 4, v124
	v_and_b32_e32 v156, 15, v124
	s_lshl_b32 s16, s2, 7
	s_nop 0
	v_lshlrev_b32_e32 v0, 3, v157
	v_or_b32_e32 v158, s16, v156
	v_ashrrev_i32_e32 v1, 31, v0
	v_lshl_add_u64 v[0:1], v[0:1], 1, s[40:41]
	v_lshlrev_b32_e32 v128, 8, v158
	v_lshl_add_u64 v[0:1], v[0:1], 0, v[128:129]
	v_add_co_u32_e32 v2, vcc, s21, v0
	v_lshlrev_b32_e32 v98, 3, v124
	s_nop 0
	v_addc_co_u32_e32 v3, vcc, 0, v1, vcc
	v_add_co_u32_e32 v4, vcc, s31, v0
	global_load_dwordx4 v[72:75], v[2:3], off offset:-4096
	global_load_dwordx4 v[68:71], v[2:3], off
	v_addc_co_u32_e32 v5, vcc, 0, v1, vcc
	v_add_co_u32_e32 v6, vcc, s28, v0
	s_lshl_b32 s17, s2, 6
	s_nop 0
	v_addc_co_u32_e32 v7, vcc, 0, v1, vcc
	global_load_dwordx4 v[64:67], v[2:3], off offset:64
	global_load_dwordx4 v[60:63], v[6:7], off offset:-4096
	global_load_dwordx4 v[76:79], v[0:1], off
	global_load_dwordx4 v[56:59], v[4:5], off offset:64
	global_load_dwordx4 v[52:55], v[6:7], off
	global_load_dwordx4 v[48:51], v[6:7], off offset:64
	v_add_co_u32_e32 v2, vcc, s36, v0
	v_and_b32_e32 v99, 56, v98
	s_nop 0
	v_addc_co_u32_e32 v3, vcc, 0, v1, vcc
	v_add_co_u32_e32 v4, vcc, s29, v0
	v_or_b32_e32 v100, s17, v99
	s_nop 0
	v_addc_co_u32_e32 v5, vcc, 0, v1, vcc
	global_load_dwordx4 v[44:47], v[6:7], off offset:128
	global_load_dwordx4 v[40:43], v[4:5], off offset:-4096
	global_load_dwordx4 v[36:39], v[2:3], off offset:64
	global_load_dwordx4 v[32:35], v[2:3], off offset:128
	global_load_dwordx4 v[28:31], v[4:5], off
	global_load_dwordx4 v[24:27], v[4:5], off offset:64
	global_load_dwordx4 v[20:23], v[4:5], off offset:128
	global_load_dwordx4 v[16:19], v[4:5], off offset:192
	v_add_co_u32_e32 v0, vcc, s37, v0
	v_lshlrev_b32_e32 v92, 2, v100
	s_nop 0
	v_addc_co_u32_e32 v1, vcc, 0, v1, vcc
	global_load_dwordx4 v[12:15], v[0:1], off
	global_load_dwordx4 v[8:11], v[0:1], off offset:64
	global_load_dwordx4 v[4:7], v[0:1], off offset:128
	s_nop 0
	global_load_dwordx4 v[0:3], v[0:1], off offset:192
	s_nop 0
	global_load_dwordx4 v[80:83], v92, s[50:51]
	global_load_dwordx4 v[84:87], v92, s[50:51] offset:16
	global_load_dwordx4 v[88:91], v92, s[0:1]
	s_nop 0
	global_load_dwordx4 v[92:95], v92, s[0:1] offset:16
	s_ashr_i32 s6, s87, 2
	s_ashr_i32 s7, s6, 31
	v_ashrrev_i32_e32 v96, 3, v124
	s_lshl_b64 s[8:9], s[6:7], 7
	v_ashrrev_i32_e32 v97, 31, v96
	v_lshl_add_u64 v[124:125], s[8:9], 0, v[96:97]
	v_lshlrev_b32_e32 v97, 8, v99
	v_lshlrev_b32_e32 v96, 1, v96
	v_add3_u32 v161, s69, v97, v96
	v_or_b32_e32 v97, 1, v99
	v_lshlrev_b32_e32 v97, 8, v97
	v_add3_u32 v163, s69, v97, v96
	v_or_b32_e32 v97, 2, v99
	v_lshlrev_b32_e32 v97, 8, v97
	v_add3_u32 v165, s69, v97, v96
	v_or_b32_e32 v97, 3, v99
	v_lshlrev_b32_e32 v97, 8, v97
	v_add3_u32 v167, s69, v97, v96
	v_or_b32_e32 v97, 4, v99
	v_lshlrev_b32_e32 v97, 8, v97
	v_add3_u32 v188, s69, v97, v96
	v_or_b32_e32 v97, 5, v99
	v_lshlrev_b32_e32 v97, 8, v97
	v_add3_u32 v190, s69, v97, v96
	v_or_b32_e32 v97, 6, v99
	v_lshlrev_b32_e32 v97, 8, v97
	v_add3_u32 v192, s69, v97, v96
	v_or_b32_e32 v97, 7, v99
	v_lshlrev_b32_e32 v97, 8, v97
	v_lshlrev_b32_e32 v128, 1, v100
	s_mov_b32 s18, 0
	v_bfe_u32 v159, v98, 4, 2
	v_and_b32_e32 v160, 8, v98
	v_bitop3_b32 v162, v99, 9, 1 bitop3:0xc8
	v_bitop3_b32 v164, v99, 10, 2 bitop3:0xc8
	v_bitop3_b32 v166, v99, 11, 3 bitop3:0xc8
	v_bitop3_b32 v187, v99, 12, 4 bitop3:0xc8
	v_bitop3_b32 v189, v99, 13, 5 bitop3:0xc8
	v_bitop3_b32 v191, v99, 14, 6 bitop3:0xc8
	v_bitop3_b32 v193, v99, 15, 7 bitop3:0xc8
	v_add3_u32 v194, s69, v97, v96
	v_lshl_add_u64 v[126:127], s[10:11], 0, v[128:129]
	s_mov_b64 s[14:15], -1
